# step3 layout + per-XCD K rotation on P1 + hoisted RMS-stat loads in the kv-up GEMM epilogue (8 loads issued up front from one base, single wait; stores no longer serialised behind per-row waits)
# speedup vs baseline: 1.0094x; 1.0001x over previous
.LBB0_1076:
	s_lshl_b32 s87, s87, 8
	s_add_i32 s87, s87, s62
	v_or_b32_e32 v148, s87, v150
	v_ashrrev_i32_e32 v149, 31, v148
	v_lshl_add_u64 v[158:159], v[148:149], 3, s[20:21]
	global_load_dword v149, v[158:159], off
	global_load_dword v238, v[158:159], off offset:128
	global_load_dword v239, v[158:159], off offset:256
	global_load_dword v240, v[158:159], off offset:384
	global_load_dword v241, v[158:159], off offset:1024
	global_load_dword v242, v[158:159], off offset:1152
	global_load_dword v243, v[158:159], off offset:1280
	global_load_dword v244, v[158:159], off offset:1408
	s_ashr_i32 s0, s87, 7
	s_and_b32 s0, s0, -16
	s_add_i32 s0, s0, s86
	s_ashr_i32 s1, s0, 31
	s_lshl_b64 s[0:1], s[0:1], 19
	s_add_u32 s42, s24, s0
	s_addc_u32 s43, s25, s1
	v_lshlrev_b32_e32 v136, 8, v148
	s_add_u32 s44, s22, s0
	v_or_b32_e32 v158, 16, v148
	v_and_b32_e32 v136, 0x7cf00, v136
	s_addc_u32 s45, s23, s1
	v_ashrrev_i32_e32 v159, 31, v158
	v_lshl_add_u64 v[164:165], s[42:43], 0, v[136:137]
	v_lshl_add_u64 v[166:167], s[44:45], 0, v[136:137]
	v_lshl_add_u64 v[160:161], v[158:159], 3, s[20:21]
	v_mov_b32_e32 v147, v137
	v_lshl_add_u64 v[164:165], v[164:165], 0, v[146:147]
	v_lshl_add_u64 v[166:167], v[166:167], 0, v[146:147]
	s_addk_i32 s87, 0x80
	s_waitcnt vmcnt(0)
	v_fmamk_f32 v149, v149, 0x3b000000, v155
	v_mul_f32_e32 v157, 0x4f800000, v149
	v_cmp_gt_f32_e32 vcc, s83, v149
	s_nop 1
	v_cndmask_b32_e32 v149, v149, v157, vcc
	v_sqrt_f32_e32 v157, v149
	s_nop 0
	v_add_u32_e32 v136, -1, v157
	v_add_u32_e32 v159, 1, v157
	v_fma_f32 v163, -v136, v157, v149
	v_fma_f32 v168, -v159, v157, v149
	v_cmp_ge_f32_e64 s[0:1], 0, v163
	s_nop 1
	v_cndmask_b32_e64 v136, v157, v136, s[0:1]
	v_cmp_lt_f32_e64 s[0:1], 0, v168
	s_nop 1
	v_cndmask_b32_e64 v136, v136, v159, s[0:1]
	v_mul_f32_e32 v157, 0x37800000, v136
	v_cndmask_b32_e32 v136, v136, v157, vcc
	v_cmp_class_f32_e32 vcc, v149, v156
	s_nop 1
	v_cndmask_b32_e32 v136, v136, v149, vcc
	v_div_scale_f32 v149, s[0:1], v136, v136, 1.0
	v_rcp_f32_e32 v157, v149
	v_div_scale_f32 v159, vcc, 1.0, v136, 1.0
	v_fma_f32 v163, -v149, v157, 1.0
	v_fmac_f32_e32 v157, v163, v157
	v_mul_f32_e32 v163, v159, v157
	v_fma_f32 v168, -v149, v163, v159
	v_fmac_f32_e32 v163, v168, v157
	v_fma_f32 v149, -v149, v163, v159
	v_div_fmas_f32 v149, v149, v157, v163
	v_div_fixup_f32 v136, v149, v136, 1.0
	v_pk_mul_f32 v[122:123], v[122:123], v[136:137] op_sel_hi:[1,0]
	v_pk_mul_f32 v[120:121], v[120:121], v[136:137] op_sel_hi:[1,0]
	v_pk_mul_f32 v[126:127], v[126:127], v[136:137] op_sel_hi:[1,0]
	v_pk_mul_f32 v[124:125], v[124:125], v[136:137] op_sel_hi:[1,0]
	v_pk_mul_f32 v[118:119], v[118:119], v[136:137] op_sel_hi:[1,0]
	v_pk_mul_f32 v[116:117], v[116:117], v[136:137] op_sel_hi:[1,0]
	v_pk_mul_f32 v[168:169], v[114:115], v[136:137] op_sel_hi:[1,0]
	v_pk_mul_f32 v[170:171], v[112:113], v[136:137] op_sel_hi:[1,0]
	v_cvt_pk_bf16_f32 v112, v120, v121
	v_cvt_pk_bf16_f32 v113, v122, v123
	v_cvt_pk_bf16_f32 v114, v124, v125
	v_cvt_pk_bf16_f32 v115, v126, v127
	v_cvt_pk_bf16_f32 v116, v116, v117
	v_cvt_pk_bf16_f32 v117, v118, v119
	v_cvt_pk_bf16_f32 v118, v170, v171
	v_cvt_pk_bf16_f32 v119, v168, v169
	global_store_dwordx4 v[164:165], v[112:115], off
	global_store_dwordx4 v[166:167], v[116:119], off
	s_nop 0
	v_or_b32_e32 v112, 32, v148
	v_ashrrev_i32_e32 v113, 31, v112
	v_lshl_add_u64 v[114:115], v[112:113], 3, s[20:21]
	v_lshlrev_b32_e32 v117, 8, v158
	v_and_b32_e32 v136, 0x7df00, v117
	v_lshl_add_u64 v[118:119], s[44:45], 0, v[136:137]
	v_lshl_add_u64 v[118:119], v[118:119], 0, v[146:147]
	s_nop 0
	v_fmamk_f32 v113, v238, 0x3b000000, v155
	v_mul_f32_e32 v116, 0x4f800000, v113
	v_cmp_gt_f32_e32 vcc, s83, v113
	s_nop 1
	v_cndmask_b32_e32 v113, v113, v116, vcc
	v_sqrt_f32_e32 v120, v113
	v_lshl_add_u64 v[116:117], s[42:43], 0, v[136:137]
	v_lshl_add_u64 v[116:117], v[116:117], 0, v[146:147]
	v_add_u32_e32 v121, -1, v120
	v_add_u32_e32 v122, 1, v120
	v_fma_f32 v123, -v121, v120, v113
	v_fma_f32 v124, -v122, v120, v113
	v_cmp_ge_f32_e64 s[0:1], 0, v123
	s_nop 1
	v_cndmask_b32_e64 v120, v120, v121, s[0:1]
	v_cmp_lt_f32_e64 s[0:1], 0, v124
	s_nop 1
	v_cndmask_b32_e64 v120, v120, v122, s[0:1]
	v_mul_f32_e32 v121, 0x37800000, v120
	v_cndmask_b32_e32 v120, v120, v121, vcc
	v_cmp_class_f32_e32 vcc, v113, v156
	s_nop 1
	v_cndmask_b32_e32 v113, v120, v113, vcc
	v_div_scale_f32 v120, s[0:1], v113, v113, 1.0
	v_rcp_f32_e32 v121, v120
	v_div_scale_f32 v122, vcc, 1.0, v113, 1.0
	v_fma_f32 v123, -v120, v121, 1.0
	v_fmac_f32_e32 v121, v123, v121
	v_mul_f32_e32 v123, v122, v121
	v_fma_f32 v124, -v120, v123, v122
	v_fmac_f32_e32 v123, v124, v121
	v_fma_f32 v120, -v120, v123, v122
	v_div_fmas_f32 v120, v120, v121, v123
	v_div_fixup_f32 v120, v120, v113, 1.0
	v_pk_mul_f32 v[110:111], v[110:111], v[120:121] op_sel_hi:[1,0]
	v_pk_mul_f32 v[108:109], v[108:109], v[120:121] op_sel_hi:[1,0]
	v_pk_mul_f32 v[106:107], v[106:107], v[120:121] op_sel_hi:[1,0]
	v_pk_mul_f32 v[104:105], v[104:105], v[120:121] op_sel_hi:[1,0]
	v_pk_mul_f32 v[102:103], v[102:103], v[120:121] op_sel_hi:[1,0]
	v_pk_mul_f32 v[100:101], v[100:101], v[120:121] op_sel_hi:[1,0]
	v_pk_mul_f32 v[122:123], v[98:99], v[120:121] op_sel_hi:[1,0]
	v_pk_mul_f32 v[120:121], v[96:97], v[120:121] op_sel_hi:[1,0]
	v_cvt_pk_bf16_f32 v96, v108, v109
	v_cvt_pk_bf16_f32 v97, v110, v111
	v_cvt_pk_bf16_f32 v98, v104, v105
	v_cvt_pk_bf16_f32 v99, v106, v107
	v_cvt_pk_bf16_f32 v100, v100, v101
	v_cvt_pk_bf16_f32 v101, v102, v103
	v_cvt_pk_bf16_f32 v102, v120, v121
	v_cvt_pk_bf16_f32 v103, v122, v123
	global_store_dwordx4 v[116:117], v[96:99], off
	global_store_dwordx4 v[118:119], v[100:103], off
	s_nop 0
	v_or_b32_e32 v96, 48, v148
	v_ashrrev_i32_e32 v97, 31, v96
	v_lshl_add_u64 v[98:99], v[96:97], 3, s[20:21]
	v_lshlrev_b32_e32 v101, 8, v112
	v_and_b32_e32 v136, 0x7ef00, v101
	v_lshl_add_u64 v[102:103], s[44:45], 0, v[136:137]
	v_lshl_add_u64 v[102:103], v[102:103], 0, v[146:147]
	s_nop 0
	v_fmamk_f32 v97, v239, 0x3b000000, v155
	v_mul_f32_e32 v100, 0x4f800000, v97
	v_cmp_gt_f32_e32 vcc, s83, v97
	s_nop 1
	v_cndmask_b32_e32 v97, v97, v100, vcc
	v_sqrt_f32_e32 v104, v97
	v_lshl_add_u64 v[100:101], s[42:43], 0, v[136:137]
	v_lshl_add_u64 v[100:101], v[100:101], 0, v[146:147]
	v_add_u32_e32 v105, -1, v104
	v_add_u32_e32 v106, 1, v104
	v_fma_f32 v107, -v105, v104, v97
	v_fma_f32 v108, -v106, v104, v97
	v_cmp_ge_f32_e64 s[0:1], 0, v107
	s_nop 1
	v_cndmask_b32_e64 v104, v104, v105, s[0:1]
	v_cmp_lt_f32_e64 s[0:1], 0, v108
	s_nop 1
	v_cndmask_b32_e64 v104, v104, v106, s[0:1]
	v_mul_f32_e32 v105, 0x37800000, v104
	v_cndmask_b32_e32 v104, v104, v105, vcc
	v_cmp_class_f32_e32 vcc, v97, v156
	s_nop 1
	v_cndmask_b32_e32 v97, v104, v97, vcc
	v_div_scale_f32 v104, s[0:1], v97, v97, 1.0
	v_rcp_f32_e32 v105, v104
	v_div_scale_f32 v106, vcc, 1.0, v97, 1.0
	v_fma_f32 v107, -v104, v105, 1.0
	v_fmac_f32_e32 v105, v107, v105
	v_mul_f32_e32 v107, v106, v105
	v_fma_f32 v108, -v104, v107, v106
	v_fmac_f32_e32 v107, v108, v105
	v_fma_f32 v104, -v104, v107, v106
	v_div_fmas_f32 v104, v104, v105, v107
	v_div_fixup_f32 v104, v104, v97, 1.0
	v_pk_mul_f32 v[94:95], v[94:95], v[104:105] op_sel_hi:[1,0]
	v_pk_mul_f32 v[92:93], v[92:93], v[104:105] op_sel_hi:[1,0]
	v_pk_mul_f32 v[90:91], v[90:91], v[104:105] op_sel_hi:[1,0]
	v_pk_mul_f32 v[88:89], v[88:89], v[104:105] op_sel_hi:[1,0]
	v_pk_mul_f32 v[86:87], v[86:87], v[104:105] op_sel_hi:[1,0]
	v_pk_mul_f32 v[84:85], v[84:85], v[104:105] op_sel_hi:[1,0]
	v_pk_mul_f32 v[106:107], v[82:83], v[104:105] op_sel_hi:[1,0]
	v_pk_mul_f32 v[104:105], v[80:81], v[104:105] op_sel_hi:[1,0]
	v_cvt_pk_bf16_f32 v80, v92, v93
	v_cvt_pk_bf16_f32 v81, v94, v95
	v_cvt_pk_bf16_f32 v82, v88, v89
	v_cvt_pk_bf16_f32 v83, v90, v91
	v_cvt_pk_bf16_f32 v84, v84, v85
	v_cvt_pk_bf16_f32 v85, v86, v87
	v_cvt_pk_bf16_f32 v86, v104, v105
	v_cvt_pk_bf16_f32 v87, v106, v107
	global_store_dwordx4 v[100:101], v[80:83], off
	global_store_dwordx4 v[102:103], v[84:87], off
	s_nop 0
	v_or_b32_e32 v80, s87, v150
	v_lshlrev_b32_e32 v82, 8, v96
	v_ashrrev_i32_e32 v81, 31, v80
	v_and_b32_e32 v136, 0x7ff00, v82
	v_lshl_add_u64 v[82:83], v[80:81], 3, s[20:21]
	v_lshl_add_u64 v[86:87], s[44:45], 0, v[136:137]
	v_lshl_add_u64 v[86:87], v[86:87], 0, v[146:147]
	s_nop 0
	v_fmamk_f32 v81, v240, 0x3b000000, v155
	v_mul_f32_e32 v84, 0x4f800000, v81
	v_cmp_gt_f32_e32 vcc, s83, v81
	s_nop 1
	v_cndmask_b32_e32 v81, v81, v84, vcc
	v_sqrt_f32_e32 v88, v81
	v_lshl_add_u64 v[84:85], s[42:43], 0, v[136:137]
	v_lshl_add_u64 v[84:85], v[84:85], 0, v[146:147]
	v_add_u32_e32 v89, -1, v88
	v_add_u32_e32 v90, 1, v88
	v_fma_f32 v91, -v89, v88, v81
	v_fma_f32 v92, -v90, v88, v81
	v_cmp_ge_f32_e64 s[0:1], 0, v91
	s_nop 1
	v_cndmask_b32_e64 v88, v88, v89, s[0:1]
	v_cmp_lt_f32_e64 s[0:1], 0, v92
	s_nop 1
	v_cndmask_b32_e64 v88, v88, v90, s[0:1]
	v_mul_f32_e32 v89, 0x37800000, v88
	v_cndmask_b32_e32 v88, v88, v89, vcc
	v_cmp_class_f32_e32 vcc, v81, v156
	s_nop 1
	v_cndmask_b32_e32 v81, v88, v81, vcc
	v_div_scale_f32 v88, s[0:1], v81, v81, 1.0
	v_rcp_f32_e32 v89, v88
	v_div_scale_f32 v90, vcc, 1.0, v81, 1.0
	s_ashr_i32 s0, s87, 7
	v_fma_f32 v91, -v88, v89, 1.0
	v_fmac_f32_e32 v89, v91, v89
	v_mul_f32_e32 v91, v90, v89
	v_fma_f32 v92, -v88, v91, v90
	v_fmac_f32_e32 v91, v92, v89
	v_fma_f32 v88, -v88, v91, v90
	v_div_fmas_f32 v88, v88, v89, v91
	v_div_fixup_f32 v88, v88, v81, 1.0
	v_pk_mul_f32 v[78:79], v[78:79], v[88:89] op_sel_hi:[1,0]
	v_pk_mul_f32 v[76:77], v[76:77], v[88:89] op_sel_hi:[1,0]
	v_pk_mul_f32 v[74:75], v[74:75], v[88:89] op_sel_hi:[1,0]
	v_pk_mul_f32 v[72:73], v[72:73], v[88:89] op_sel_hi:[1,0]
	v_pk_mul_f32 v[70:71], v[70:71], v[88:89] op_sel_hi:[1,0]
	v_pk_mul_f32 v[68:69], v[68:69], v[88:89] op_sel_hi:[1,0]
	v_pk_mul_f32 v[90:91], v[66:67], v[88:89] op_sel_hi:[1,0]
	v_pk_mul_f32 v[88:89], v[64:65], v[88:89] op_sel_hi:[1,0]
	v_cvt_pk_bf16_f32 v64, v76, v77
	v_cvt_pk_bf16_f32 v65, v78, v79
	v_cvt_pk_bf16_f32 v66, v72, v73
	v_cvt_pk_bf16_f32 v67, v74, v75
	v_cvt_pk_bf16_f32 v68, v68, v69
	v_cvt_pk_bf16_f32 v69, v70, v71
	v_cvt_pk_bf16_f32 v70, v88, v89
	v_cvt_pk_bf16_f32 v71, v90, v91
	global_store_dwordx4 v[84:85], v[64:67], off
	global_store_dwordx4 v[86:87], v[68:71], off
	s_nop 0
	v_or_b32_e32 v64, 16, v80
	v_lshlrev_b32_e32 v66, 8, v80
	v_ashrrev_i32_e32 v65, 31, v64
	v_and_b32_e32 v136, 0x7cf00, v66
	v_lshl_add_u64 v[66:67], v[64:65], 3, s[20:21]
	s_and_b32 s0, s0, -16
	s_add_i32 s0, s0, s86
	s_ashr_i32 s1, s0, 31
	s_lshl_b64 s[0:1], s[0:1], 19
	s_add_u32 s44, s24, s0
	s_addc_u32 s45, s25, s1
	s_add_u32 s42, s22, s0
	s_addc_u32 s43, s23, s1
	v_lshl_add_u64 v[68:69], s[44:45], 0, v[136:137]
	v_lshl_add_u64 v[68:69], v[68:69], 0, v[146:147]
	s_nop 0
	v_fmamk_f32 v65, v241, 0x3b000000, v155
	v_mul_f32_e32 v70, 0x4f800000, v65
	v_cmp_gt_f32_e32 vcc, s83, v65
	s_nop 1
	v_cndmask_b32_e32 v65, v65, v70, vcc
	v_sqrt_f32_e32 v72, v65
	v_lshl_add_u64 v[70:71], s[42:43], 0, v[136:137]
	v_lshl_add_u64 v[70:71], v[70:71], 0, v[146:147]
	v_add_u32_e32 v73, -1, v72
	v_add_u32_e32 v74, 1, v72
	v_fma_f32 v75, -v73, v72, v65
	v_fma_f32 v76, -v74, v72, v65
	v_cmp_ge_f32_e64 s[0:1], 0, v75
	s_nop 1
	v_cndmask_b32_e64 v72, v72, v73, s[0:1]
	v_cmp_lt_f32_e64 s[0:1], 0, v76
	s_nop 1
	v_cndmask_b32_e64 v72, v72, v74, s[0:1]
	v_mul_f32_e32 v73, 0x37800000, v72
	v_cndmask_b32_e32 v72, v72, v73, vcc
	v_cmp_class_f32_e32 vcc, v65, v156
	s_nop 1
	v_cndmask_b32_e32 v65, v72, v65, vcc
	v_div_scale_f32 v72, s[0:1], v65, v65, 1.0
	v_rcp_f32_e32 v73, v72
	v_div_scale_f32 v74, vcc, 1.0, v65, 1.0
	v_fma_f32 v75, -v72, v73, 1.0
	v_fmac_f32_e32 v73, v75, v73
	v_mul_f32_e32 v75, v74, v73
	v_fma_f32 v76, -v72, v75, v74
	v_fmac_f32_e32 v75, v76, v73
	v_fma_f32 v72, -v72, v75, v74
	v_div_fmas_f32 v72, v72, v73, v75
	v_div_fixup_f32 v72, v72, v65, 1.0
	v_pk_mul_f32 v[62:63], v[62:63], v[72:73] op_sel_hi:[1,0]
	v_pk_mul_f32 v[60:61], v[60:61], v[72:73] op_sel_hi:[1,0]
	v_pk_mul_f32 v[58:59], v[58:59], v[72:73] op_sel_hi:[1,0]
	v_pk_mul_f32 v[56:57], v[56:57], v[72:73] op_sel_hi:[1,0]
	v_pk_mul_f32 v[54:55], v[54:55], v[72:73] op_sel_hi:[1,0]
	v_pk_mul_f32 v[52:53], v[52:53], v[72:73] op_sel_hi:[1,0]
	v_pk_mul_f32 v[74:75], v[50:51], v[72:73] op_sel_hi:[1,0]
	v_pk_mul_f32 v[72:73], v[48:49], v[72:73] op_sel_hi:[1,0]
	v_cvt_pk_bf16_f32 v48, v60, v61
	v_cvt_pk_bf16_f32 v49, v62, v63
	v_cvt_pk_bf16_f32 v50, v56, v57
	v_cvt_pk_bf16_f32 v51, v58, v59
	v_cvt_pk_bf16_f32 v52, v52, v53
	v_cvt_pk_bf16_f32 v53, v54, v55
	v_cvt_pk_bf16_f32 v54, v72, v73
	v_cvt_pk_bf16_f32 v55, v74, v75
	global_store_dwordx4 v[68:69], v[48:51], off
	global_store_dwordx4 v[70:71], v[52:55], off
	s_nop 0
	v_or_b32_e32 v48, 32, v80
	v_ashrrev_i32_e32 v49, 31, v48
	v_lshl_add_u64 v[50:51], v[48:49], 3, s[20:21]
	v_lshlrev_b32_e32 v53, 8, v64
	v_and_b32_e32 v136, 0x7ff00, v53
	v_lshl_add_u64 v[54:55], s[42:43], 0, v[136:137]
	v_lshl_add_u64 v[54:55], v[54:55], 0, v[146:147]
	s_nop 0
	v_fmamk_f32 v49, v242, 0x3b000000, v155
	v_mul_f32_e32 v52, 0x4f800000, v49
	v_cmp_gt_f32_e32 vcc, s83, v49
	s_nop 1
	v_cndmask_b32_e32 v49, v49, v52, vcc
	v_sqrt_f32_e32 v56, v49
	v_lshl_add_u64 v[52:53], s[44:45], 0, v[136:137]
	v_lshl_add_u64 v[52:53], v[52:53], 0, v[146:147]
	v_add_u32_e32 v57, -1, v56
	v_add_u32_e32 v58, 1, v56
	v_fma_f32 v59, -v57, v56, v49
	v_fma_f32 v60, -v58, v56, v49
	v_cmp_ge_f32_e64 s[0:1], 0, v59
	s_nop 1
	v_cndmask_b32_e64 v56, v56, v57, s[0:1]
	v_cmp_lt_f32_e64 s[0:1], 0, v60
	s_nop 1
	v_cndmask_b32_e64 v56, v56, v58, s[0:1]
	v_mul_f32_e32 v57, 0x37800000, v56
	v_cndmask_b32_e32 v56, v56, v57, vcc
	v_cmp_class_f32_e32 vcc, v49, v156
	s_nop 1
	v_cndmask_b32_e32 v49, v56, v49, vcc
	v_div_scale_f32 v56, s[0:1], v49, v49, 1.0
	v_rcp_f32_e32 v57, v56
	v_div_scale_f32 v58, vcc, 1.0, v49, 1.0
	v_fma_f32 v59, -v56, v57, 1.0
	v_fmac_f32_e32 v57, v59, v57
	v_mul_f32_e32 v59, v58, v57
	v_fma_f32 v60, -v56, v59, v58
	v_fmac_f32_e32 v59, v60, v57
	v_fma_f32 v56, -v56, v59, v58
	v_div_fmas_f32 v56, v56, v57, v59
	v_div_fixup_f32 v56, v56, v49, 1.0
	v_pk_mul_f32 v[46:47], v[46:47], v[56:57] op_sel_hi:[1,0]
	v_pk_mul_f32 v[44:45], v[44:45], v[56:57] op_sel_hi:[1,0]
	v_pk_mul_f32 v[42:43], v[42:43], v[56:57] op_sel_hi:[1,0]
	v_pk_mul_f32 v[40:41], v[40:41], v[56:57] op_sel_hi:[1,0]
	v_pk_mul_f32 v[38:39], v[38:39], v[56:57] op_sel_hi:[1,0]
	v_pk_mul_f32 v[36:37], v[36:37], v[56:57] op_sel_hi:[1,0]
	v_pk_mul_f32 v[58:59], v[34:35], v[56:57] op_sel_hi:[1,0]
	v_pk_mul_f32 v[56:57], v[32:33], v[56:57] op_sel_hi:[1,0]
	v_cvt_pk_bf16_f32 v32, v44, v45
	v_cvt_pk_bf16_f32 v33, v46, v47
	v_cvt_pk_bf16_f32 v34, v40, v41
	v_cvt_pk_bf16_f32 v35, v42, v43
	v_cvt_pk_bf16_f32 v36, v36, v37
	v_cvt_pk_bf16_f32 v37, v38, v39
	v_cvt_pk_bf16_f32 v38, v56, v57
	v_cvt_pk_bf16_f32 v39, v58, v59
	global_store_dwordx4 v[52:53], v[32:35], off
	global_store_dwordx4 v[54:55], v[36:39], off
	s_nop 0
	v_or_b32_e32 v32, 48, v80
	v_ashrrev_i32_e32 v33, 31, v32
	v_lshl_add_u64 v[34:35], v[32:33], 3, s[20:21]
	v_lshlrev_b32_e32 v37, 8, v48
	v_and_b32_e32 v136, 0x7ff00, v37
	v_lshl_add_u64 v[38:39], s[42:43], 0, v[136:137]
	v_lshl_add_u64 v[38:39], v[38:39], 0, v[146:147]
	s_nop 0
	v_fmamk_f32 v33, v243, 0x3b000000, v155
	v_mul_f32_e32 v36, 0x4f800000, v33
	v_cmp_gt_f32_e32 vcc, s83, v33
	s_nop 1
	v_cndmask_b32_e32 v33, v33, v36, vcc
	v_sqrt_f32_e32 v40, v33
	v_lshl_add_u64 v[36:37], s[44:45], 0, v[136:137]
	v_lshl_add_u64 v[36:37], v[36:37], 0, v[146:147]
	v_add_u32_e32 v41, -1, v40
	v_add_u32_e32 v42, 1, v40
	v_fma_f32 v43, -v41, v40, v33
	v_fma_f32 v44, -v42, v40, v33
	v_cmp_ge_f32_e64 s[0:1], 0, v43
	s_nop 1
	v_cndmask_b32_e64 v40, v40, v41, s[0:1]
	v_cmp_lt_f32_e64 s[0:1], 0, v44
	s_nop 1
	v_cndmask_b32_e64 v40, v40, v42, s[0:1]
	v_mul_f32_e32 v41, 0x37800000, v40
	v_cndmask_b32_e32 v40, v40, v41, vcc
	v_cmp_class_f32_e32 vcc, v33, v156
	s_nop 1
	v_cndmask_b32_e32 v33, v40, v33, vcc
	v_div_scale_f32 v40, s[0:1], v33, v33, 1.0
	v_rcp_f32_e32 v41, v40
	v_div_scale_f32 v42, vcc, 1.0, v33, 1.0
	v_fma_f32 v43, -v40, v41, 1.0
	v_fmac_f32_e32 v41, v43, v41
	v_mul_f32_e32 v43, v42, v41
	v_fma_f32 v44, -v40, v43, v42
	v_fmac_f32_e32 v43, v44, v41
	v_fma_f32 v40, -v40, v43, v42
	v_div_fmas_f32 v40, v40, v41, v43
	v_div_fixup_f32 v40, v40, v33, 1.0
	v_pk_mul_f32 v[30:31], v[30:31], v[40:41] op_sel_hi:[1,0]
	v_pk_mul_f32 v[28:29], v[28:29], v[40:41] op_sel_hi:[1,0]
	v_pk_mul_f32 v[26:27], v[26:27], v[40:41] op_sel_hi:[1,0]
	v_pk_mul_f32 v[24:25], v[24:25], v[40:41] op_sel_hi:[1,0]
	v_pk_mul_f32 v[22:23], v[22:23], v[40:41] op_sel_hi:[1,0]
	v_pk_mul_f32 v[20:21], v[20:21], v[40:41] op_sel_hi:[1,0]
	v_pk_mul_f32 v[42:43], v[18:19], v[40:41] op_sel_hi:[1,0]
	v_pk_mul_f32 v[40:41], v[16:17], v[40:41] op_sel_hi:[1,0]
	v_cvt_pk_bf16_f32 v16, v28, v29
	v_cvt_pk_bf16_f32 v17, v30, v31
	v_cvt_pk_bf16_f32 v18, v24, v25
	v_cvt_pk_bf16_f32 v19, v26, v27
	v_cvt_pk_bf16_f32 v20, v20, v21
	v_cvt_pk_bf16_f32 v21, v22, v23
	v_cvt_pk_bf16_f32 v22, v40, v41
	v_cvt_pk_bf16_f32 v23, v42, v43
	global_store_dwordx4 v[36:37], v[16:19], off
	global_store_dwordx4 v[38:39], v[20:23], off
	s_nop 0
	v_lshlrev_b32_e32 v17, 8, v32
	v_and_b32_e32 v136, 0x7ff00, v17
	v_lshl_add_u64 v[18:19], s[42:43], 0, v[136:137]
	v_lshl_add_u64 v[18:19], v[18:19], 0, v[146:147]
	s_nop 0
	v_fmamk_f32 v16, v244, 0x3b000000, v155
	v_mul_f32_e32 v17, 0x4f800000, v16
	v_cmp_gt_f32_e32 vcc, s83, v16
	s_nop 1
	v_cndmask_b32_e32 v20, v16, v17, vcc
	v_sqrt_f32_e32 v21, v20
	v_lshl_add_u64 v[16:17], s[44:45], 0, v[136:137]
	v_lshl_add_u64 v[16:17], v[16:17], 0, v[146:147]
	v_add_u32_e32 v22, -1, v21
	v_add_u32_e32 v23, 1, v21
	v_fma_f32 v24, -v22, v21, v20
	v_fma_f32 v25, -v23, v21, v20
	v_cmp_ge_f32_e64 s[0:1], 0, v24
	s_nop 1
	v_cndmask_b32_e64 v21, v21, v22, s[0:1]
	v_cmp_lt_f32_e64 s[0:1], 0, v25
	s_nop 1
	v_cndmask_b32_e64 v21, v21, v23, s[0:1]
	v_mul_f32_e32 v22, 0x37800000, v21
	v_cndmask_b32_e32 v21, v21, v22, vcc
	v_cmp_class_f32_e32 vcc, v20, v156
	s_nop 1
	v_cndmask_b32_e32 v20, v21, v20, vcc
	v_div_scale_f32 v21, s[0:1], v20, v20, 1.0
	v_rcp_f32_e32 v22, v21
	v_div_scale_f32 v23, vcc, 1.0, v20, 1.0
	s_mov_b64 s[0:1], -1
	v_fma_f32 v24, -v21, v22, 1.0
	v_fmac_f32_e32 v22, v24, v22
	v_mul_f32_e32 v24, v23, v22
	v_fma_f32 v25, -v21, v24, v23
	v_fmac_f32_e32 v24, v25, v22
	v_fma_f32 v21, -v21, v24, v23
	v_div_fmas_f32 v21, v21, v22, v24
	v_div_fixup_f32 v20, v21, v20, 1.0
	v_pk_mul_f32 v[14:15], v[14:15], v[20:21] op_sel_hi:[1,0]
	v_pk_mul_f32 v[12:13], v[12:13], v[20:21] op_sel_hi:[1,0]
	v_pk_mul_f32 v[10:11], v[10:11], v[20:21] op_sel_hi:[1,0]
	v_pk_mul_f32 v[8:9], v[8:9], v[20:21] op_sel_hi:[1,0]
	v_pk_mul_f32 v[6:7], v[6:7], v[20:21] op_sel_hi:[1,0]
	v_pk_mul_f32 v[4:5], v[4:5], v[20:21] op_sel_hi:[1,0]
	v_pk_mul_f32 v[22:23], v[2:3], v[20:21] op_sel_hi:[1,0]
	v_pk_mul_f32 v[20:21], v[0:1], v[20:21] op_sel_hi:[1,0]
	v_cvt_pk_bf16_f32 v0, v12, v13
	v_cvt_pk_bf16_f32 v1, v14, v15
	v_cvt_pk_bf16_f32 v2, v8, v9
	v_cvt_pk_bf16_f32 v3, v10, v11
	v_cvt_pk_bf16_f32 v4, v4, v5
	v_cvt_pk_bf16_f32 v5, v6, v7
	v_cvt_pk_bf16_f32 v6, v20, v21
	v_cvt_pk_bf16_f32 v7, v22, v23
	global_store_dwordx4 v[16:17], v[0:3], off
	global_store_dwordx4 v[18:19], v[4:7], off
	s_and_b64 vcc, exec, s[6:7]
	s_cbranch_vccnz .LBB0_1060
	s_andn2_b64 vcc, exec, s[28:29]
	s_cbranch_vccnz .LBB0_1059
	s_barrier
	s_branch .LBB0_1059
